# diff-attention main loop: next step's first QK MFMA issued before the step-end barrier (overlap across segment boundary); rescale block re-issues it
# baseline (speedup 1.0000x reference)
.LBB0_494:
	v_mfma_f32_32x32x16_bf16 v[116:131], v[192:195], v[160:163], 0
.Lattn_head2:
	s_lshl_b32 s6, s6, 1
	v_add_u32_e32 v231, s6, v252
	ds_read_b64_tr_b16 v[196:197], v231 offset:24576
	ds_read_b64_tr_b16 v[198:199], v231 offset:25088
	s_waitcnt lgkmcnt(9)
	v_add_f32_e32 v100, v84, v85
	v_add_f32_e32 v100, v86, v100
	v_add_f32_e32 v100, v87, v100
	v_add_f32_e32 v100, v88, v100
	v_add_f32_e32 v132, v89, v100
	v_cvt_pk_bf16_f32 v144, v84, v85
	v_cvt_pk_bf16_f32 v145, v86, v87
	ds_read_b64_tr_b16 v[84:85], v231 offset:28672
	ds_read_b64_tr_b16 v[86:87], v231 offset:29184
	s_waitcnt lgkmcnt(10)
	v_mfma_f32_32x32x16_bf16 v[100:115], v[188:191], v[160:163], 0
	v_add_f32_e32 v132, v90, v132
	v_add_f32_e32 v132, v91, v132
	v_add_f32_e32 v132, v92, v132
	v_add_f32_e32 v132, v93, v132
	v_cvt_pk_bf16_f32 v146, v88, v89
	v_cvt_pk_bf16_f32 v147, v90, v91
	ds_read_b64_tr_b16 v[88:89], v231 offset:32768
	ds_read_b64_tr_b16 v[90:91], v231 offset:33280
	s_waitcnt lgkmcnt(11)
	v_mfma_f32_32x32x16_bf16 v[116:131], v[184:187], v[156:159], v[116:131]
	v_add_f32_e32 v132, v94, v132
	v_add_f32_e32 v132, v95, v132
	v_add_f32_e32 v132, v96, v132
	v_add_f32_e32 v132, v97, v132
	v_cvt_pk_bf16_f32 v140, v92, v93
	v_cvt_pk_bf16_f32 v141, v94, v95
	ds_read_b64_tr_b16 v[92:93], v231 offset:36864
	ds_read_b64_tr_b16 v[94:95], v231 offset:37376
	s_waitcnt lgkmcnt(12)
	v_mfma_f32_32x32x16_bf16 v[100:115], v[180:183], v[156:159], v[100:115]
	v_add_f32_e32 v132, v98, v132
	v_add_f32_e32 v132, v99, v132
	v_add_f32_e32 v132, v68, v132
	v_add_f32_e32 v132, v69, v132
	v_cvt_pk_bf16_f32 v142, v96, v97
	v_cvt_pk_bf16_f32 v143, v98, v99
	ds_read_b64_tr_b16 v[96:97], v231 offset:25600
	ds_read_b64_tr_b16 v[98:99], v231 offset:26112
	s_waitcnt lgkmcnt(13)
	v_mfma_f32_32x32x16_bf16 v[116:131], v[176:179], v[152:155], v[116:131]
	v_add_f32_e32 v132, v70, v132
	v_add_f32_e32 v132, v71, v132
	v_add_f32_e32 v132, v72, v132
	v_add_f32_e32 v132, v73, v132
	v_cvt_pk_bf16_f32 v136, v68, v69
	v_cvt_pk_bf16_f32 v137, v70, v71
	ds_read_b64_tr_b16 v[68:69], v231 offset:29696
	ds_read_b64_tr_b16 v[70:71], v231 offset:30208
	s_waitcnt lgkmcnt(14)
	v_mfma_f32_32x32x16_bf16 v[100:115], v[172:175], v[152:155], v[100:115]
	v_add_f32_e32 v132, v74, v132
	v_add_f32_e32 v132, v75, v132
	v_add_f32_e32 v132, v76, v132
	v_add_f32_e32 v132, v77, v132
	v_cvt_pk_bf16_f32 v138, v72, v73
	v_cvt_pk_bf16_f32 v139, v74, v75
	ds_read_b64_tr_b16 v[72:73], v231 offset:33792
	ds_read_b64_tr_b16 v[74:75], v231 offset:34304
	s_waitcnt lgkmcnt(14)
	v_mfma_f32_32x32x16_bf16 v[116:131], v[168:171], v[148:151], v[116:131]
	v_add_f32_e32 v132, v78, v132
	v_add_f32_e32 v132, v79, v132
	v_add_f32_e32 v132, v80, v132
	v_add_f32_e32 v168, v81, v132
	v_cvt_pk_bf16_f32 v132, v76, v77
	v_cvt_pk_bf16_f32 v133, v78, v79
	ds_read_b64_tr_b16 v[76:77], v231 offset:37888
	ds_read_b64_tr_b16 v[78:79], v231 offset:38400
	v_mfma_f32_32x32x16_bf16 v[100:115], v[164:167], v[148:151], v[100:115]
	v_add_f32_e32 v134, v82, v168
	v_add_f32_e32 v134, v83, v134
	v_add_f32_e32 v164, 0, v134
	v_cvt_pk_bf16_f32 v134, v80, v81
	v_cvt_pk_bf16_f32 v135, v82, v83
	v_cndmask_b32_e64 v80, 0, 1, s[4:5]
	v_add_f32_e32 v192, v229, v164
	v_cmp_ne_u32_e64 s[10:11], 1, v80
	s_andn2_b64 vcc, exec, s[4:5]
	s_mov_b64 s[6:7], 0
	s_cbranch_vccz .LBB0_502
.LBB0_495:
	s_waitcnt lgkmcnt(14)
	v_mfma_f32_32x32x16_bf16 v[52:67], v[144:147], v[196:199], v[52:67]
	v_exp_f32_e32 v116, v116
	v_exp_f32_e32 v117, v117
	ds_read_b64_tr_b16 v[80:81], v231 offset:26624
	ds_read_b64_tr_b16 v[82:83], v231 offset:27136
	s_waitcnt lgkmcnt(14)
	v_mfma_f32_32x32x16_bf16 v[36:51], v[144:147], v[84:87], v[36:51]
	v_exp_f32_e32 v118, v118
	v_exp_f32_e32 v119, v119
	ds_read_b64_tr_b16 v[84:85], v231 offset:30720
	ds_read_b64_tr_b16 v[86:87], v231 offset:31232
	s_waitcnt lgkmcnt(14)
	v_mfma_f32_32x32x16_bf16 v[20:35], v[144:147], v[88:91], v[20:35]
	v_exp_f32_e32 v120, v120
	v_exp_f32_e32 v121, v121
	ds_read_b64_tr_b16 v[88:89], v231 offset:34816
	ds_read_b64_tr_b16 v[90:91], v231 offset:35328
	s_waitcnt lgkmcnt(14)
	v_mfma_f32_32x32x16_bf16 v[4:19], v[144:147], v[92:95], v[4:19]
	v_exp_f32_e32 v122, v122
	v_exp_f32_e32 v123, v123
	ds_read_b64_tr_b16 v[92:93], v231 offset:38912
	ds_read_b64_tr_b16 v[94:95], v231 offset:39424
	s_waitcnt lgkmcnt(14)
	v_mfma_f32_32x32x16_bf16 v[52:67], v[140:143], v[96:99], v[52:67]
	v_exp_f32_e32 v124, v124
	v_exp_f32_e32 v125, v125
	ds_read_b64_tr_b16 v[96:97], v231 offset:27648
	ds_read_b64_tr_b16 v[98:99], v231 offset:28160
	s_waitcnt lgkmcnt(14)
	v_mfma_f32_32x32x16_bf16 v[36:51], v[140:143], v[68:71], v[36:51]
	v_exp_f32_e32 v126, v126
	v_exp_f32_e32 v127, v127
	ds_read_b64_tr_b16 v[188:189], v231 offset:31744
	ds_read_b64_tr_b16 v[190:191], v231 offset:32256
	s_waitcnt lgkmcnt(14)
	v_mfma_f32_32x32x16_bf16 v[20:35], v[140:143], v[72:75], v[20:35]
	v_exp_f32_e32 v128, v128
	v_exp_f32_e32 v129, v129
	ds_read_b64_tr_b16 v[206:207], v231 offset:35840
	ds_read_b64_tr_b16 v[208:209], v231 offset:36352
	s_waitcnt lgkmcnt(14)
	v_mfma_f32_32x32x16_bf16 v[4:19], v[140:143], v[76:79], v[4:19]
	v_exp_f32_e32 v130, v130
	v_exp_f32_e32 v131, v131
	ds_read_b64_tr_b16 v[76:77], v231 offset:39936
	ds_read_b64_tr_b16 v[78:79], v231 offset:40448
	s_waitcnt lgkmcnt(14)
	v_mfma_f32_32x32x16_bf16 v[52:67], v[136:139], v[80:83], v[52:67]
	v_exp_f32_e32 v100, v100
	v_exp_f32_e32 v101, v101
	v_add_u32_e32 v80, s26, v251
	ds_read_b128 v[72:75], v80
	ds_read_b128 v[68:71], v80 offset:512
	s_waitcnt lgkmcnt(14)
	v_mfma_f32_32x32x16_bf16 v[36:51], v[136:139], v[84:87], v[36:51]
	v_exp_f32_e32 v102, v102
	v_exp_f32_e32 v103, v103
	ds_read_b128 v[184:187], v80 offset:2048
	ds_read_b128 v[180:183], v80 offset:2560
	s_waitcnt lgkmcnt(14)
	v_mfma_f32_32x32x16_bf16 v[20:35], v[136:139], v[88:91], v[20:35]
	v_exp_f32_e32 v104, v104
	v_exp_f32_e32 v105, v105
	ds_read_b128 v[176:179], v80 offset:4096
	ds_read_b128 v[172:175], v80 offset:4608
	s_waitcnt lgkmcnt(14)
	v_mfma_f32_32x32x16_bf16 v[4:19], v[136:139], v[92:95], v[4:19]
	v_exp_f32_e32 v106, v106
	v_exp_f32_e32 v107, v107
	ds_read_b128 v[168:171], v80 offset:6144
	ds_read_b128 v[164:167], v80 offset:6656
	s_waitcnt lgkmcnt(14)
	v_mfma_f32_32x32x16_bf16 v[52:67], v[132:135], v[96:99], v[52:67]
	v_exp_f32_e32 v108, v108
	v_exp_f32_e32 v109, v109
	s_add_i32 m0, s38, s31
	v_lshl_add_u64 v[198:199], s[2:3], 0, v[200:201]
	v_lshl_add_u64 v[80:81], v[198:199], 0, s[84:85]
	global_load_lds_dwordx4 v[80:81], off
	s_waitcnt lgkmcnt(12)
	v_mfma_f32_32x32x16_bf16 v[36:51], v[132:135], v[188:191], v[36:51]
	v_exp_f32_e32 v110, v110
	v_exp_f32_e32 v111, v111
	s_lshl_b32 s41, s26, 1
	s_add_i32 m0, s41, s34
	v_lshl_add_u64 v[196:197], s[2:3], 0, v[202:203]
	v_lshl_add_u64 v[80:81], v[196:197], 0, s[86:87]
	global_load_lds_dwordx4 v[80:81], off
	s_waitcnt lgkmcnt(10)
	v_mfma_f32_32x32x16_bf16 v[20:35], v[132:135], v[206:209], v[20:35]
	v_exp_f32_e32 v112, v112
	v_exp_f32_e32 v113, v113
	s_add_i32 m0, m0, 0x2000
	v_lshl_add_u64 v[80:81], v[196:197], 0, s[88:89]
	global_load_lds_dwordx4 v[80:81], off
	s_waitcnt lgkmcnt(8)
	v_mfma_f32_32x32x16_bf16 v[4:19], v[132:135], v[76:79], v[4:19]
	v_exp_f32_e32 v114, v114
	v_exp_f32_e32 v115, v115
	s_waitcnt vmcnt(3) lgkmcnt(0)
	v_mfma_f32_32x32x16_bf16 v[84:99], v[72:75], v[160:163], 0
	s_barrier
	s_andn2_b64 vcc, exec, s[6:7]
	s_cbranch_vccnz .LBB0_497
	s_waitcnt lgkmcnt(0)
	s_nop 7
	s_nop 7
	v_add_u32_e32 v88, s29, v204
	ds_read_b128 v[76:79], v88 offset:96
	ds_read_b128 v[80:83], v88 offset:64
	ds_read_b128 v[84:87], v88 offset:32
	ds_read_b128 v[88:91], v88
	s_waitcnt lgkmcnt(3)
	v_pk_mul_f32 v[64:65], v[64:65], v[76:77]
	s_waitcnt lgkmcnt(2)
	v_pk_mul_f32 v[60:61], v[60:61], v[80:81]
	s_waitcnt lgkmcnt(1)
	v_pk_mul_f32 v[56:57], v[56:57], v[84:85]
	v_pk_mul_f32 v[66:67], v[66:67], v[78:79]
	v_pk_mul_f32 v[62:63], v[62:63], v[82:83]
	v_pk_mul_f32 v[58:59], v[58:59], v[86:87]
	s_waitcnt lgkmcnt(0)
	v_pk_mul_f32 v[54:55], v[54:55], v[90:91]
	v_pk_mul_f32 v[52:53], v[52:53], v[88:89]
	v_pk_mul_f32 v[48:49], v[48:49], v[76:77]
	v_pk_mul_f32 v[44:45], v[44:45], v[80:81]
	v_pk_mul_f32 v[40:41], v[40:41], v[84:85]
	v_pk_mul_f32 v[50:51], v[50:51], v[78:79]
	v_pk_mul_f32 v[46:47], v[46:47], v[82:83]
	v_pk_mul_f32 v[42:43], v[42:43], v[86:87]
	v_pk_mul_f32 v[38:39], v[38:39], v[90:91]
	v_pk_mul_f32 v[36:37], v[36:37], v[88:89]
	v_pk_mul_f32 v[32:33], v[32:33], v[76:77]
	v_pk_mul_f32 v[28:29], v[28:29], v[80:81]
	v_pk_mul_f32 v[24:25], v[24:25], v[84:85]
	v_pk_mul_f32 v[34:35], v[34:35], v[78:79]
	v_pk_mul_f32 v[30:31], v[30:31], v[82:83]
	v_pk_mul_f32 v[26:27], v[26:27], v[86:87]
	v_pk_mul_f32 v[22:23], v[22:23], v[90:91]
	v_pk_mul_f32 v[20:21], v[20:21], v[88:89]
	v_pk_mul_f32 v[16:17], v[16:17], v[76:77]
	v_pk_mul_f32 v[12:13], v[12:13], v[80:81]
	v_pk_mul_f32 v[8:9], v[8:9], v[84:85]
	v_pk_mul_f32 v[18:19], v[18:19], v[78:79]
	v_pk_mul_f32 v[14:15], v[14:15], v[82:83]
	v_pk_mul_f32 v[10:11], v[10:11], v[86:87]
	v_pk_mul_f32 v[6:7], v[6:7], v[90:91]
	v_pk_mul_f32 v[4:5], v[4:5], v[88:89]
	v_mfma_f32_32x32x16_bf16 v[84:99], v[72:75], v[160:163], 0
.LBB0_497:
	s_lshl_b32 s6, s38, 1
	v_add_u32_e32 v193, s6, v252
	ds_read_b64_tr_b16 v[188:189], v193 offset:24576
	ds_read_b64_tr_b16 v[190:191], v193 offset:25088
	s_waitcnt lgkmcnt(9)
	v_add_f32_e32 v76, v116, v117
	v_add_f32_e32 v72, v118, v76
	v_add_f32_e32 v72, v119, v72
	v_add_f32_e32 v72, v120, v72
	v_add_f32_e32 v132, v121, v72
	v_cvt_pk_bf16_f32 v144, v116, v117
	v_cvt_pk_bf16_f32 v145, v118, v119
	ds_read_b64_tr_b16 v[116:117], v193 offset:28672
	ds_read_b64_tr_b16 v[118:119], v193 offset:29184
	s_waitcnt lgkmcnt(10)
	v_mfma_f32_32x32x16_bf16 v[68:83], v[68:71], v[160:163], 0
	v_add_f32_e32 v132, v122, v132
	v_add_f32_e32 v132, v123, v132
	v_add_f32_e32 v132, v124, v132
	v_add_f32_e32 v132, v125, v132
	v_cvt_pk_bf16_f32 v146, v120, v121
	v_cvt_pk_bf16_f32 v147, v122, v123
	ds_read_b64_tr_b16 v[120:121], v193 offset:32768
	ds_read_b64_tr_b16 v[122:123], v193 offset:33280
	s_waitcnt lgkmcnt(11)
	v_mfma_f32_32x32x16_bf16 v[84:99], v[184:187], v[156:159], v[84:99]
	v_add_f32_e32 v132, v126, v132
	v_add_f32_e32 v132, v127, v132
	v_add_f32_e32 v132, v128, v132
	v_add_f32_e32 v132, v129, v132
	v_cvt_pk_bf16_f32 v140, v124, v125
	v_cvt_pk_bf16_f32 v141, v126, v127
	ds_read_b64_tr_b16 v[124:125], v193 offset:36864
	ds_read_b64_tr_b16 v[126:127], v193 offset:37376
	s_waitcnt lgkmcnt(12)
	v_mfma_f32_32x32x16_bf16 v[68:83], v[180:183], v[156:159], v[68:83]
	v_add_f32_e32 v132, v130, v132
	v_add_f32_e32 v132, v131, v132
	v_add_f32_e32 v132, v100, v132
	v_add_f32_e32 v132, v101, v132
	v_cvt_pk_bf16_f32 v142, v128, v129
	v_cvt_pk_bf16_f32 v143, v130, v131
	ds_read_b64_tr_b16 v[128:129], v193 offset:25600
	ds_read_b64_tr_b16 v[130:131], v193 offset:26112
	s_waitcnt lgkmcnt(13)
	v_mfma_f32_32x32x16_bf16 v[84:99], v[176:179], v[152:155], v[84:99]
	v_add_f32_e32 v132, v102, v132
	v_add_f32_e32 v132, v103, v132
	v_add_f32_e32 v132, v104, v132
	v_add_f32_e32 v132, v105, v132
	v_cvt_pk_bf16_f32 v136, v100, v101
	v_cvt_pk_bf16_f32 v137, v102, v103
	ds_read_b64_tr_b16 v[100:101], v193 offset:29696
	ds_read_b64_tr_b16 v[102:103], v193 offset:30208
	s_waitcnt lgkmcnt(14)
	v_mfma_f32_32x32x16_bf16 v[68:83], v[172:175], v[152:155], v[68:83]
	v_add_f32_e32 v132, v106, v132
	v_add_f32_e32 v132, v107, v132
	v_add_f32_e32 v132, v108, v132
	v_add_f32_e32 v132, v109, v132
	v_cvt_pk_bf16_f32 v138, v104, v105
	v_cvt_pk_bf16_f32 v139, v106, v107
	ds_read_b64_tr_b16 v[104:105], v193 offset:33792
	ds_read_b64_tr_b16 v[106:107], v193 offset:34304
	s_waitcnt lgkmcnt(14)
	v_mfma_f32_32x32x16_bf16 v[84:99], v[168:171], v[148:151], v[84:99]
	v_add_f32_e32 v132, v110, v132
	v_add_f32_e32 v132, v111, v132
	v_add_f32_e32 v132, v112, v132
	v_add_f32_e32 v168, v113, v132
	v_cvt_pk_bf16_f32 v132, v108, v109
	v_cvt_pk_bf16_f32 v133, v110, v111
	ds_read_b64_tr_b16 v[108:109], v193 offset:37888
	ds_read_b64_tr_b16 v[110:111], v193 offset:38400
	v_mfma_f32_32x32x16_bf16 v[68:83], v[164:167], v[148:151], v[68:83]
	v_add_f32_e32 v134, v114, v168
	v_add_f32_e32 v134, v115, v134
	v_add_f32_e32 v164, 0, v134
	v_cvt_pk_bf16_f32 v134, v112, v113
	v_cvt_pk_bf16_f32 v135, v114, v115
	s_nop 0
	v_add_f32_e32 v229, v192, v164
	s_and_b64 vcc, exec, s[10:11]
	s_mov_b64 s[6:7], 0
	s_cbranch_vccz .LBB0_505
.LBB0_498:
	s_add_i32 s12, s26, 0x2000
	s_cmpk_lg_i32 s26, 0x4000
	s_cselect_b32 s38, s12, 0
	s_waitcnt lgkmcnt(14)
	v_mfma_f32_32x32x16_bf16 v[52:67], v[144:147], v[188:191], v[52:67]
	v_exp_f32_e32 v84, v84
	v_exp_f32_e32 v85, v85
	ds_read_b64_tr_b16 v[112:113], v193 offset:26624
	ds_read_b64_tr_b16 v[114:115], v193 offset:27136
	s_waitcnt lgkmcnt(14)
	v_mfma_f32_32x32x16_bf16 v[36:51], v[144:147], v[116:119], v[36:51]
	v_exp_f32_e32 v86, v86
	v_exp_f32_e32 v87, v87
	ds_read_b64_tr_b16 v[116:117], v193 offset:30720
	ds_read_b64_tr_b16 v[118:119], v193 offset:31232
	s_waitcnt lgkmcnt(14)
	v_mfma_f32_32x32x16_bf16 v[20:35], v[144:147], v[120:123], v[20:35]
	v_exp_f32_e32 v88, v88
	v_exp_f32_e32 v89, v89
	ds_read_b64_tr_b16 v[120:121], v193 offset:34816
	ds_read_b64_tr_b16 v[122:123], v193 offset:35328
	s_waitcnt lgkmcnt(14)
	v_mfma_f32_32x32x16_bf16 v[4:19], v[144:147], v[124:127], v[4:19]
	v_exp_f32_e32 v90, v90
	v_exp_f32_e32 v91, v91
	ds_read_b64_tr_b16 v[124:125], v193 offset:38912
	ds_read_b64_tr_b16 v[126:127], v193 offset:39424
	s_waitcnt lgkmcnt(14)
	v_mfma_f32_32x32x16_bf16 v[52:67], v[140:143], v[128:131], v[52:67]
	v_exp_f32_e32 v92, v92
	v_exp_f32_e32 v93, v93
	ds_read_b64_tr_b16 v[128:129], v193 offset:27648
	ds_read_b64_tr_b16 v[130:131], v193 offset:28160
	s_waitcnt lgkmcnt(14)
	v_mfma_f32_32x32x16_bf16 v[36:51], v[140:143], v[100:103], v[36:51]
	v_exp_f32_e32 v94, v94
	v_exp_f32_e32 v95, v95
	ds_read_b64_tr_b16 v[100:101], v193 offset:31744
	ds_read_b64_tr_b16 v[102:103], v193 offset:32256
	s_waitcnt lgkmcnt(14)
	v_mfma_f32_32x32x16_bf16 v[20:35], v[140:143], v[104:107], v[20:35]
	v_exp_f32_e32 v96, v96
	v_exp_f32_e32 v97, v97
	ds_read_b64_tr_b16 v[104:105], v193 offset:35840
	ds_read_b64_tr_b16 v[106:107], v193 offset:36352
	s_waitcnt lgkmcnt(14)
	v_mfma_f32_32x32x16_bf16 v[4:19], v[140:143], v[108:111], v[4:19]
	v_exp_f32_e32 v98, v98
	v_exp_f32_e32 v99, v99
	ds_read_b64_tr_b16 v[108:109], v193 offset:39936
	ds_read_b64_tr_b16 v[110:111], v193 offset:40448
	s_waitcnt lgkmcnt(14)
	v_mfma_f32_32x32x16_bf16 v[52:67], v[136:139], v[112:115], v[52:67]
	v_exp_f32_e32 v68, v68
	v_exp_f32_e32 v69, v69
	v_add_u32_e32 v112, s38, v251
	ds_read_b128 v[192:195], v112
	ds_read_b128 v[188:191], v112 offset:512
	s_waitcnt lgkmcnt(14)
	v_mfma_f32_32x32x16_bf16 v[36:51], v[136:139], v[116:119], v[36:51]
	v_exp_f32_e32 v70, v70
	v_exp_f32_e32 v71, v71
	ds_read_b128 v[184:187], v112 offset:2048
	ds_read_b128 v[180:183], v112 offset:2560
	s_waitcnt lgkmcnt(14)
	v_mfma_f32_32x32x16_bf16 v[20:35], v[136:139], v[120:123], v[20:35]
	v_exp_f32_e32 v72, v72
	v_exp_f32_e32 v73, v73
	ds_read_b128 v[176:179], v112 offset:4096
	ds_read_b128 v[172:175], v112 offset:4608
	s_waitcnt lgkmcnt(14)
	v_mfma_f32_32x32x16_bf16 v[4:19], v[136:139], v[124:127], v[4:19]
	v_exp_f32_e32 v74, v74
	v_exp_f32_e32 v75, v75
	ds_read_b128 v[168:171], v112 offset:6144
	ds_read_b128 v[164:167], v112 offset:6656
	s_waitcnt lgkmcnt(14)
	v_mfma_f32_32x32x16_bf16 v[52:67], v[132:135], v[128:131], v[52:67]
	v_exp_f32_e32 v76, v76
	v_exp_f32_e32 v77, v77
	s_add_i32 m0, s26, s31
	v_lshl_add_u64 v[112:113], v[198:199], 0, s[90:91]
	global_load_lds_dwordx4 v[112:113], off
	s_waitcnt lgkmcnt(12)
	v_mfma_f32_32x32x16_bf16 v[36:51], v[132:135], v[100:103], v[36:51]
	v_exp_f32_e32 v78, v78
	v_exp_f32_e32 v79, v79
	s_lshl_b32 s12, s38, 1
	s_add_i32 m0, s12, s34
	v_lshl_add_u64 v[100:101], v[196:197], 0, s[92:93]
	global_load_lds_dwordx4 v[100:101], off
	s_waitcnt lgkmcnt(10)
	v_mfma_f32_32x32x16_bf16 v[20:35], v[132:135], v[104:107], v[20:35]
	v_exp_f32_e32 v80, v80
	v_exp_f32_e32 v81, v81
	s_add_i32 m0, m0, 0x2000
	v_lshl_add_u64 v[100:101], v[196:197], 0, s[94:95]
	global_load_lds_dwordx4 v[100:101], off
	s_waitcnt lgkmcnt(8)
	v_mfma_f32_32x32x16_bf16 v[4:19], v[132:135], v[108:111], v[4:19]
	v_exp_f32_e32 v82, v82
	v_exp_f32_e32 v83, v83
	s_waitcnt vmcnt(3) lgkmcnt(0)
	v_mfma_f32_32x32x16_bf16 v[116:131], v[192:195], v[160:163], 0
	s_barrier
	s_andn2_b64 vcc, exec, s[6:7]
	s_cbranch_vccnz .LBB0_500
	s_waitcnt lgkmcnt(0)
	v_add_u32_e32 v112, s29, v204
	ds_read_b128 v[100:103], v112 offset:96
	ds_read_b128 v[104:107], v112 offset:64
	ds_read_b128 v[108:111], v112 offset:32
	ds_read_b128 v[112:115], v112
	s_waitcnt lgkmcnt(3)
	v_pk_mul_f32 v[64:65], v[64:65], v[100:101]
	s_waitcnt lgkmcnt(2)
	v_pk_mul_f32 v[60:61], v[60:61], v[104:105]
	s_waitcnt lgkmcnt(1)
	v_pk_mul_f32 v[56:57], v[56:57], v[108:109]
	v_pk_mul_f32 v[66:67], v[66:67], v[102:103]
	v_pk_mul_f32 v[62:63], v[62:63], v[106:107]
	v_pk_mul_f32 v[58:59], v[58:59], v[110:111]
	s_waitcnt lgkmcnt(0)
	v_pk_mul_f32 v[54:55], v[54:55], v[114:115]
	v_pk_mul_f32 v[52:53], v[52:53], v[112:113]
	v_pk_mul_f32 v[48:49], v[48:49], v[100:101]
	v_pk_mul_f32 v[44:45], v[44:45], v[104:105]
	v_pk_mul_f32 v[40:41], v[40:41], v[108:109]
	v_pk_mul_f32 v[50:51], v[50:51], v[102:103]
	v_pk_mul_f32 v[46:47], v[46:47], v[106:107]
	v_pk_mul_f32 v[42:43], v[42:43], v[110:111]
	v_pk_mul_f32 v[38:39], v[38:39], v[114:115]
	v_pk_mul_f32 v[36:37], v[36:37], v[112:113]
	v_pk_mul_f32 v[32:33], v[32:33], v[100:101]
	v_pk_mul_f32 v[28:29], v[28:29], v[104:105]
	v_pk_mul_f32 v[24:25], v[24:25], v[108:109]
	v_pk_mul_f32 v[34:35], v[34:35], v[102:103]
	v_pk_mul_f32 v[30:31], v[30:31], v[106:107]
	v_pk_mul_f32 v[26:27], v[26:27], v[110:111]
	v_pk_mul_f32 v[22:23], v[22:23], v[114:115]
	v_pk_mul_f32 v[20:21], v[20:21], v[112:113]
	v_pk_mul_f32 v[16:17], v[16:17], v[100:101]
	v_pk_mul_f32 v[12:13], v[12:13], v[104:105]
	v_pk_mul_f32 v[8:9], v[8:9], v[108:109]
	v_pk_mul_f32 v[18:19], v[18:19], v[102:103]
	v_pk_mul_f32 v[14:15], v[14:15], v[106:107]
	v_pk_mul_f32 v[10:11], v[10:11], v[110:111]
	v_pk_mul_f32 v[6:7], v[6:7], v[114:115]
	v_pk_mul_f32 v[4:5], v[4:5], v[112:113]
